# v155 + odd XCD-local workgroups start the two gate phases ~5us late (two-group stagger of the load bursts)
# baseline (speedup 1.0000x reference)
.LBB0_20:
	s_mov_b32 s1, 0x84
	s_lshr_b32 s1, s1, s18
	s_and_b32 s1, s1, 1
	s_cmp_eq_u32 s1, 0
	s_cbranch_scc1 .Lskew_done
	v_readlane_b32 s0, v252, 8
	s_lshr_b32 s0, s0, 3
	s_and_b32 s0, s0, 1
	s_mul_i32 s0, s0, 160
	s_cmp_eq_u32 s0, 0
	s_cbranch_scc1 .Lskew_done
.Lskew_loop:
	s_sleep 1
	s_sub_u32 s0, s0, 1
	s_cmp_lg_u32 s0, 0
	s_cbranch_scc1 .Lskew_loop
